# sample attention: next page's page-table entry requested one page ahead; grid barrier leader: no trailing waits after the release atomics
# speedup vs baseline: 1.0138x; 1.0002x over previous
.LBB0_1610:
	s_add_i32 s42, s1, s40
	s_add_i32 s52, s42, s41
	s_ashr_i32 s53, s52, 31
	s_lshl_b64 s[52:53], s[52:53], 2
	s_add_u32 s52, s50, s52
	s_addc_u32 s53, s51, s53
	s_cmp_lg_u32 s1, 0
	s_cbranch_scc1 .Lpt_have
	global_load_dword v246, v137, s[52:53]
.Lpt_have:
	s_cmp_lt_u32 s1, 3
	s_cselect_b32 s32, 4, 0
	s_add_u32 s90, s52, s32
	s_addc_u32 s91, s53, 0
	v_mov_b32_e32 v145, v48
	v_mov_b32_e32 v144, v49
	v_mov_b32_e32 v143, v50
	v_mov_b32_e32 v142, v51
	v_add_u32_e32 v146, 0x800, v203
	s_waitcnt vmcnt(0)
	v_readfirstlane_b32 s52, v246
	global_load_dword v246, v137, s[90:91]
	s_ashr_i32 s53, s52, 31
	s_lshl_b64 s[54:55], s[52:53], 17
	s_add_u32 s54, s54, s10
	s_addc_u32 s55, s55, s11
	s_lshl_b64 s[54:55], s[54:55], 2
	s_add_u32 s88, s4, s54
	s_addc_u32 s89, s5, s55
	v_lshl_add_u64 v[112:113], s[88:89], 0, v[136:137]
	v_add_co_u32_e32 v48, vcc, s44, v112
	s_lshl_b32 s48, s42, 7
	s_nop 0
	v_addc_co_u32_e32 v49, vcc, 0, v113, vcc
	v_add_co_u32_e32 v50, vcc, s49, v112
	v_or_b32_e32 v86, s48, v180
	s_nop 0
	v_addc_co_u32_e32 v51, vcc, 0, v113, vcc
	v_add_co_u32_e32 v52, vcc, s56, v112
	global_load_dwordx4 v[76:79], v[112:113], off nt
	global_load_dwordx4 v[68:71], v[48:49], off nt
	global_load_dwordx4 v[60:63], v[50:51], off nt
	v_addc_co_u32_e32 v53, vcc, 0, v113, vcc
	v_add_co_u32_e32 v54, vcc, s57, v112
	v_sub_u32_e32 v150, v198, v86
	s_nop 0
	v_addc_co_u32_e32 v55, vcc, 0, v113, vcc
	v_add_co_u32_e32 v56, vcc, s58, v112
	v_sub_u32_e32 v151, v199, v86
	s_nop 0
	v_addc_co_u32_e32 v57, vcc, 0, v113, vcc
	v_add_co_u32_e32 v58, vcc, s59, v112
	v_sub_u32_e32 v149, v200, v86
	s_nop 0
	v_addc_co_u32_e32 v59, vcc, 0, v113, vcc
	v_add_co_u32_e32 v84, vcc, s60, v112
	global_load_dwordx4 v[72:75], v[52:53], off nt
	global_load_dwordx4 v[64:67], v[54:55], off nt
	s_nop 0
	global_load_dwordx4 v[52:55], v[56:57], off nt
	global_load_dwordx4 v[48:51], v[58:59], off nt
	v_addc_co_u32_e32 v85, vcc, 0, v113, vcc
	global_load_dwordx4 v[56:59], v[84:85], off nt
	v_add_co_u32_e32 v80, vcc, s61, v112
	v_sub_u32_e32 v148, v201, v86
	s_nop 0
	v_addc_co_u32_e32 v81, vcc, 0, v113, vcc
	v_add_co_u32_e32 v82, vcc, s62, v112
	s_mov_b32 s42, 0x20000
	s_nop 0
	v_addc_co_u32_e32 v83, vcc, 0, v113, vcc
	v_add_co_u32_e32 v98, vcc, s63, v112
	v_cvt_f32_i32_e32 v150, v150
	s_nop 0
	v_addc_co_u32_e32 v99, vcc, 0, v113, vcc
	v_add_co_u32_e32 v92, vcc, s64, v112
	global_load_dwordx4 v[88:91], v[80:81], off nt
	global_load_dwordx4 v[84:87], v[82:83], off nt
	s_nop 0
	global_load_dwordx4 v[80:83], v[98:99], off nt
	v_addc_co_u32_e32 v93, vcc, 0, v113, vcc
	v_add_co_u32_e32 v94, vcc, s65, v112
	global_load_dwordx4 v[104:107], v[92:93], off nt
	s_nop 0
	v_addc_co_u32_e32 v95, vcc, 0, v113, vcc
	v_add_co_u32_e32 v96, vcc, s66, v112
	v_cvt_f32_i32_e32 v151, v151
	s_nop 0
	v_addc_co_u32_e32 v97, vcc, 0, v113, vcc
	v_add_co_u32_e32 v114, vcc, s67, v112
	v_cvt_f32_i32_e32 v149, v149
	s_nop 0
	v_addc_co_u32_e32 v115, vcc, 0, v113, vcc
	v_add_co_u32_e32 v130, vcc, s68, v112
	v_cvt_f32_i32_e32 v148, v148
	s_nop 0
	v_addc_co_u32_e32 v131, vcc, 0, v113, vcc
	global_load_dwordx4 v[108:111], v[94:95], off nt
	global_load_dwordx4 v[100:103], v[96:97], off nt
	s_nop 0
	global_load_dwordx4 v[96:99], v[114:115], off nt
	global_load_dwordx4 v[92:95], v[130:131], off nt
	v_add_co_u32_e32 v152, vcc, s42, v112
	s_mov_b32 s42, 0x22000
	s_nop 0
	v_addc_co_u32_e32 v153, vcc, 0, v113, vcc
	v_add_co_u32_e32 v154, vcc, s42, v112
	s_mov_b32 s42, 0x24000
	s_nop 0
	v_addc_co_u32_e32 v155, vcc, 0, v113, vcc
	v_add_co_u32_e32 v156, vcc, s42, v112
	s_mov_b32 s42, 0x26000
	s_nop 0
	v_addc_co_u32_e32 v157, vcc, 0, v113, vcc
	v_add_co_u32_e32 v132, vcc, s42, v112
	s_mov_b32 s42, 0x28000
	s_nop 0
	v_addc_co_u32_e32 v133, vcc, 0, v113, vcc
	v_add_co_u32_e32 v158, vcc, s42, v112
	s_waitcnt vmcnt(15)
	v_cvt_pk_bf16_f32 v76, v76, v77
	v_cvt_pk_bf16_f32 v77, v78, v79
	s_waitcnt vmcnt(14)
	v_cvt_pk_bf16_f32 v68, v68, v69
	v_cvt_pk_bf16_f32 v69, v70, v71
	v_addc_co_u32_e32 v159, vcc, 0, v113, vcc
	s_mov_b32 s42, 0x2a000
	s_waitcnt vmcnt(13)
	v_cvt_pk_bf16_f32 v60, v60, v61
	v_cvt_pk_bf16_f32 v61, v62, v63
	v_add_co_u32_e32 v134, vcc, s42, v112
	s_waitcnt vmcnt(12)
	v_cvt_pk_bf16_f32 v62, v72, v73
	v_cvt_pk_bf16_f32 v63, v74, v75
	s_waitcnt vmcnt(11)
	v_cvt_pk_bf16_f32 v64, v64, v65
	v_cvt_pk_bf16_f32 v65, v66, v67
	s_waitcnt vmcnt(10)
	v_cvt_pk_bf16_f32 v52, v52, v53
	v_cvt_pk_bf16_f32 v53, v54, v55
	s_waitcnt vmcnt(9)
	v_cvt_pk_bf16_f32 v48, v48, v49
	v_cvt_pk_bf16_f32 v49, v50, v51
	s_waitcnt vmcnt(8)
	v_cvt_pk_bf16_f32 v50, v56, v57
	v_cvt_pk_bf16_f32 v51, v58, v59
	ds_write2_b64 v203, v[76:77], v[68:69] offset1:68
	ds_write2_b64 v203, v[60:61], v[62:63] offset0:136 offset1:204
	ds_write2_b64 v146, v[64:65], v[52:53] offset0:16 offset1:84
	ds_write2_b64 v146, v[48:49], v[50:51] offset0:152 offset1:220
	s_waitcnt lgkmcnt(0)
	v_addc_co_u32_e32 v135, vcc, 0, v113, vcc
	s_mov_b32 s42, 0x2c000
	v_add_co_u32_e32 v160, vcc, s42, v112
	ds_read_b128 v[52:55], v204
	ds_read_b128 v[56:59], v204 offset:64
	ds_read_b128 v[60:63], v204 offset:128
	ds_read_b128 v[64:67], v204 offset:192
	s_waitcnt lgkmcnt(0)
	v_addc_co_u32_e32 v161, vcc, 0, v113, vcc
	s_mov_b32 s42, 0x2e000
	v_add_co_u32_e32 v164, vcc, s42, v112
	global_load_dwordx4 v[68:71], v[152:153], off nt
	global_load_dwordx4 v[72:75], v[154:155], off nt
	global_load_dwordx4 v[48:51], v[156:157], off nt
	v_addc_co_u32_e32 v165, vcc, 0, v113, vcc
	global_load_dwordx4 v[76:79], v[132:133], off nt
	global_load_dwordx4 v[152:155], v[158:159], off nt
	s_nop 0
	global_load_dwordx4 v[156:159], v[134:135], off nt
	s_nop 0
	global_load_dwordx4 v[160:163], v[160:161], off nt
	s_nop 0
	global_load_dwordx4 v[164:167], v[164:165], off nt
	s_mov_b32 s42, 0x30000
	v_add_co_u32_e32 v114, vcc, s42, v112
	s_mov_b32 s42, 0x32000
	s_nop 0
	v_addc_co_u32_e32 v115, vcc, 0, v113, vcc
	v_add_co_u32_e32 v130, vcc, s42, v112
	s_waitcnt vmcnt(15)
	v_cvt_pk_bf16_f32 v88, v88, v89
	v_cvt_pk_bf16_f32 v89, v90, v91
	s_waitcnt vmcnt(14)
	v_cvt_pk_bf16_f32 v84, v84, v85
	v_cvt_pk_bf16_f32 v85, v86, v87
	v_addc_co_u32_e32 v131, vcc, 0, v113, vcc
	s_mov_b32 s42, 0x34000
	s_waitcnt vmcnt(13)
	v_cvt_pk_bf16_f32 v80, v80, v81
	v_cvt_pk_bf16_f32 v81, v82, v83
	s_waitcnt vmcnt(12)
	v_cvt_pk_bf16_f32 v82, v104, v105
	v_cvt_pk_bf16_f32 v83, v106, v107
	s_waitcnt vmcnt(11)
	v_cvt_pk_bf16_f32 v86, v108, v109
	v_cvt_pk_bf16_f32 v87, v110, v111
	s_waitcnt vmcnt(10)
	v_cvt_pk_bf16_f32 v90, v100, v101
	v_cvt_pk_bf16_f32 v91, v102, v103
	s_waitcnt vmcnt(9)
	v_cvt_pk_bf16_f32 v96, v96, v97
	v_cvt_pk_bf16_f32 v97, v98, v99
	s_waitcnt vmcnt(8)
	v_cvt_pk_bf16_f32 v92, v92, v93
	v_cvt_pk_bf16_f32 v93, v94, v95
	ds_write2_b64 v203, v[88:89], v[84:85] offset1:68
	ds_write2_b64 v203, v[80:81], v[82:83] offset0:136 offset1:204
	ds_write2_b64 v146, v[86:87], v[90:91] offset0:16 offset1:84
	ds_write2_b64 v146, v[96:97], v[92:93] offset0:152 offset1:220
	s_waitcnt lgkmcnt(7)
	v_mfma_f32_16x16x32_bf16 v[52:55], v[4:7], v[52:55], 0
	v_add_co_u32_e32 v140, vcc, s42, v112
	s_waitcnt lgkmcnt(0)
	s_mov_b32 s42, 0x36000
	s_nop 0
	v_addc_co_u32_e32 v141, vcc, 0, v113, vcc
	v_add_co_u32_e32 v168, vcc, s42, v112
	ds_read_b128 v[80:83], v204
	s_nop 0
	v_addc_co_u32_e32 v169, vcc, 0, v113, vcc
	s_mov_b32 s42, 0x38000
	s_waitcnt lgkmcnt(7)
	v_mfma_f32_16x16x32_bf16 v[52:55], v[0:3], v[56:59], v[52:55]
	v_add_co_u32_e32 v132, vcc, s42, v112
	s_mov_b32 s42, 0x3a000
	s_nop 0
	v_addc_co_u32_e32 v133, vcc, 0, v113, vcc
	v_add_co_u32_e32 v134, vcc, s42, v112
	ds_read_b128 v[56:59], v204 offset:64
	s_nop 0
	v_addc_co_u32_e32 v135, vcc, 0, v113, vcc
	s_mov_b32 s42, 0x3c000
	s_waitcnt lgkmcnt(1)
	v_mfma_f32_16x16x32_bf16 v[80:83], v[4:7], v[80:83], 0
	v_add_co_u32_e32 v170, vcc, s42, v112
	s_mov_b32 s42, 0x3e000
	v_mfma_f32_16x16x32_bf16 v[52:55], v[12:15], v[60:63], v[52:55]
	v_addc_co_u32_e32 v171, vcc, 0, v113, vcc
	ds_read_b128 v[60:63], v204 offset:128
	ds_read_b128 v[84:87], v204 offset:192
	s_waitcnt lgkmcnt(0)
	v_add_co_u32_e32 v172, vcc, s42, v112
	s_waitcnt lgkmcnt(2)
	v_mfma_f32_16x16x32_bf16 v[56:59], v[0:3], v[56:59], v[80:83]
	v_addc_co_u32_e32 v173, vcc, 0, v113, vcc
	s_nop 1
	global_load_dwordx4 v[80:83], v[114:115], off nt
	global_load_dwordx4 v[88:91], v[130:131], off nt
	global_load_dwordx4 v[92:95], v[140:141], off nt
	global_load_dwordx4 v[96:99], v[168:169], off nt
	v_mfma_f32_16x16x32_bf16 v[52:55], v[8:11], v[64:67], v[52:55]
	global_load_dwordx4 v[64:67], v[132:133], off nt
	global_load_dwordx4 v[100:103], v[134:135], off nt
	global_load_dwordx4 v[104:107], v[170:171], off nt
	global_load_dwordx4 v[108:111], v[172:173], off nt
	v_or_b32_e32 v147, s48, v184
	v_sub_u32_e32 v174, v198, v147
	s_waitcnt lgkmcnt(1)
	v_mfma_f32_16x16x32_bf16 v[56:59], v[12:15], v[60:63], v[56:59]
	s_waitcnt vmcnt(13)
	v_cvt_pk_bf16_f32 v48, v48, v49
	v_cvt_pk_bf16_f32 v49, v50, v51
	s_waitcnt vmcnt(12)
	v_cvt_pk_bf16_f32 v50, v76, v77
	v_cvt_pk_bf16_f32 v51, v78, v79
	ds_write2_b64 v203, v[48:49], v[50:51] offset0:136 offset1:204
	s_waitcnt vmcnt(11)
	v_cvt_pk_bf16_f32 v48, v152, v153
	v_cvt_pk_bf16_f32 v49, v154, v155
	s_waitcnt vmcnt(10)
	v_cvt_pk_bf16_f32 v50, v156, v157
	v_cvt_pk_bf16_f32 v51, v158, v159
	v_fma_f32 v135, -v177, v150, v52
	v_fma_f32 v133, -v177, v151, v53
	v_fma_f32 v130, -v177, v149, v54
	v_fma_f32 v131, -v177, v148, v55
	s_waitcnt lgkmcnt(1)
	v_mfma_f32_16x16x32_bf16 v[52:55], v[8:11], v[84:87], v[56:59]
	ds_write2_b64 v146, v[48:49], v[50:51] offset0:16 offset1:84
	s_waitcnt vmcnt(9)
	v_cvt_pk_bf16_f32 v48, v160, v161
	v_cvt_pk_bf16_f32 v49, v162, v163
	v_cvt_pk_bf16_f32 v56, v68, v69
	v_cvt_pk_bf16_f32 v57, v70, v71
	v_cvt_pk_bf16_f32 v58, v72, v73
	v_cvt_pk_bf16_f32 v59, v74, v75
	s_waitcnt vmcnt(8)
	v_cvt_pk_bf16_f32 v50, v164, v165
	v_cvt_pk_bf16_f32 v51, v166, v167
	ds_write2_b64 v203, v[56:57], v[58:59] offset1:68
	ds_write2_b64 v146, v[48:49], v[50:51] offset0:152 offset1:220
	s_waitcnt lgkmcnt(0)
	ds_read_b128 v[56:59], v204
	ds_read_b128 v[60:63], v204 offset:64
	s_waitcnt lgkmcnt(1)
	v_mfma_f32_16x16x32_bf16 v[56:59], v[4:7], v[56:59], 0
	ds_read_b128 v[68:71], v204 offset:128
	v_cvt_f32_i32_e32 v174, v174
	v_sub_u32_e32 v48, v199, v147
	s_waitcnt lgkmcnt(1)
	v_mfma_f32_16x16x32_bf16 v[56:59], v[0:3], v[60:63], v[56:59]
	v_sub_u32_e32 v50, v200, v147
	v_cvt_f32_i32_e32 v48, v48
	v_cvt_f32_i32_e32 v51, v50
	v_sub_u32_e32 v50, v201, v147
	ds_read_b128 v[60:63], v204 offset:192
	v_fma_f32 v49, -v177, v174, v52
	v_cvt_f32_i32_e32 v52, v50
	s_waitcnt lgkmcnt(1)
	v_mfma_f32_16x16x32_bf16 v[56:59], v[12:15], v[68:71], v[56:59]
	v_fma_f32 v50, -v177, v48, v53
	v_or_b32_e32 v48, s48, v185
	v_fma_f32 v51, -v177, v51, v54
	v_fma_f32 v132, -v177, v52, v55
	s_waitcnt lgkmcnt(0)
	v_mfma_f32_16x16x32_bf16 v[52:55], v[8:11], v[60:63], v[56:59]
	s_mov_b32 s42, 0x40000
	s_waitcnt lgkmcnt(0)
	s_add_u32 s54, s6, s54
	s_addc_u32 s55, s7, s55
	v_sub_u32_e32 v56, v198, v48
	v_cvt_f32_i32_e32 v134, v56
	v_add_co_u32_e32 v56, vcc, s42, v112
	s_mov_b32 s42, 0x42000
	s_nop 0
	v_addc_co_u32_e32 v57, vcc, 0, v113, vcc
	v_add_co_u32_e32 v60, vcc, s42, v112
	s_mov_b32 s42, 0x44000
	s_nop 0
	v_addc_co_u32_e32 v61, vcc, 0, v113, vcc
	v_add_co_u32_e32 v68, vcc, s42, v112
	s_mov_b32 s42, 0x46000
	s_nop 0
	v_addc_co_u32_e32 v69, vcc, 0, v113, vcc
	v_add_co_u32_e32 v72, vcc, s42, v112
	s_mov_b32 s42, 0x48000
	s_nop 0
	v_addc_co_u32_e32 v73, vcc, 0, v113, vcc
	v_add_co_u32_e32 v76, vcc, s42, v112
	s_mov_b32 s42, 0x4a000
	s_nop 0
	v_addc_co_u32_e32 v77, vcc, 0, v113, vcc
	v_add_co_u32_e32 v84, vcc, s42, v112
	s_mov_b32 s42, 0x4c000
	s_nop 0
	v_addc_co_u32_e32 v85, vcc, 0, v113, vcc
	global_load_dwordx4 v[56:59], v[56:57], off nt
	s_nop 0
	global_load_dwordx4 v[60:63], v[60:61], off nt
	v_add_co_u32_e32 v114, vcc, s42, v112
	global_load_dwordx4 v[68:71], v[68:69], off nt
	s_nop 0
	global_load_dwordx4 v[72:75], v[72:73], off nt
	v_addc_co_u32_e32 v115, vcc, 0, v113, vcc
	s_mov_b32 s42, 0x4e000
	global_load_dwordx4 v[76:79], v[76:77], off nt
	s_nop 0
	global_load_dwordx4 v[84:87], v[84:85], off nt
	v_add_co_u32_e32 v140, vcc, s42, v112
	s_waitcnt vmcnt(13)
	v_cvt_pk_bf16_f32 v80, v80, v81
	v_addc_co_u32_e32 v141, vcc, 0, v113, vcc
	global_load_dwordx4 v[148:151], v[114:115], off nt
	global_load_dwordx4 v[152:155], v[140:141], off nt
	v_cvt_pk_bf16_f32 v81, v82, v83
	s_waitcnt vmcnt(14)
	v_cvt_pk_bf16_f32 v82, v88, v89
	v_cvt_pk_bf16_f32 v83, v90, v91
	s_waitcnt vmcnt(11)
	v_cvt_pk_bf16_f32 v64, v64, v65
	v_cvt_pk_bf16_f32 v65, v66, v67
	s_waitcnt vmcnt(10)
	v_cvt_pk_bf16_f32 v66, v100, v101
	v_cvt_pk_bf16_f32 v67, v102, v103
	ds_write2_b64 v203, v[80:81], v[82:83] offset1:68
	v_cvt_pk_bf16_f32 v80, v92, v93
	v_cvt_pk_bf16_f32 v81, v94, v95
	v_cvt_pk_bf16_f32 v82, v96, v97
	v_cvt_pk_bf16_f32 v83, v98, v99
	ds_write2_b64 v146, v[64:65], v[66:67] offset0:16 offset1:84
	s_waitcnt vmcnt(9)
	v_cvt_pk_bf16_f32 v64, v104, v105
	v_cvt_pk_bf16_f32 v65, v106, v107
	s_waitcnt vmcnt(8)
	v_cvt_pk_bf16_f32 v66, v108, v109
	v_cvt_pk_bf16_f32 v67, v110, v111
	ds_write2_b64 v203, v[80:81], v[82:83] offset0:136 offset1:204
	ds_write2_b64 v146, v[64:65], v[66:67] offset0:152 offset1:220
	s_waitcnt lgkmcnt(0)
	ds_read_b128 v[64:67], v204
	ds_read_b128 v[80:83], v204 offset:64
	s_waitcnt lgkmcnt(1)
	v_mfma_f32_16x16x32_bf16 v[64:67], v[4:7], v[64:67], 0
	v_sub_u32_e32 v88, v200, v48
	v_cvt_f32_i32_e32 v92, v88
	ds_read_b128 v[88:91], v204 offset:128
	s_waitcnt lgkmcnt(1)
	v_mfma_f32_16x16x32_bf16 v[64:67], v[0:3], v[80:83], v[64:67]
	v_fma_f32 v147, -v177, v134, v52
	v_sub_u32_e32 v52, v199, v48
	v_sub_u32_e32 v48, v201, v48
	v_cvt_f32_i32_e32 v48, v48
	ds_read_b128 v[80:83], v204 offset:192
	v_cvt_f32_i32_e32 v52, v52
	s_waitcnt lgkmcnt(1)
	v_mfma_f32_16x16x32_bf16 v[64:67], v[12:15], v[88:91], v[64:67]
	v_fma_f32 v134, -v177, v48, v55
	v_or_b32_e32 v48, s48, v186
	v_fma_f32 v141, -v177, v52, v53
	v_fma_f32 v140, -v177, v92, v54
	s_waitcnt lgkmcnt(0)
	v_mfma_f32_16x16x32_bf16 v[52:55], v[8:11], v[80:83], v[64:67]
	s_mov_b32 s42, 0x50000
	s_waitcnt lgkmcnt(0)
	s_lshl_b64 s[52:53], s[52:53], 19
	s_waitcnt vmcnt(7)
	v_cvt_pk_bf16_f32 v56, v56, v57
	v_sub_u32_e32 v64, v198, v48
	v_cvt_f32_i32_e32 v114, v64
	v_add_co_u32_e32 v64, vcc, s42, v112
	s_mov_b32 s42, 0x52000
	s_nop 0
	v_addc_co_u32_e32 v65, vcc, 0, v113, vcc
	v_add_co_u32_e32 v80, vcc, s42, v112
	s_mov_b32 s42, 0x54000
	s_nop 0
	v_addc_co_u32_e32 v81, vcc, 0, v113, vcc
	v_add_co_u32_e32 v88, vcc, s42, v112
	s_mov_b32 s42, 0x56000
	s_nop 0
	v_addc_co_u32_e32 v89, vcc, 0, v113, vcc
	v_add_co_u32_e32 v92, vcc, s42, v112
	s_mov_b32 s42, 0x58000
	s_nop 0
	v_addc_co_u32_e32 v93, vcc, 0, v113, vcc
	v_add_co_u32_e32 v96, vcc, s42, v112
	global_load_dwordx4 v[64:67], v[64:65], off nt
	s_nop 0
	global_load_dwordx4 v[80:83], v[80:81], off nt
	v_addc_co_u32_e32 v97, vcc, 0, v113, vcc
	s_mov_b32 s42, 0x5a000
	global_load_dwordx4 v[88:91], v[88:89], off nt
	s_nop 0
	global_load_dwordx4 v[92:95], v[92:93], off nt
	v_add_co_u32_e32 v100, vcc, s42, v112
	s_mov_b32 s42, 0x5c000
	s_nop 0
	v_addc_co_u32_e32 v101, vcc, 0, v113, vcc
	global_load_dwordx4 v[96:99], v[96:97], off nt
	s_nop 0
	global_load_dwordx4 v[100:103], v[100:101], off nt
	v_add_co_u32_e32 v104, vcc, s42, v112
	s_mov_b32 s42, 0x5e000
	s_nop 0
	v_addc_co_u32_e32 v105, vcc, 0, v113, vcc
	v_add_co_u32_e32 v108, vcc, s42, v112
	v_cvt_pk_bf16_f32 v57, v58, v59
	s_nop 0
	v_addc_co_u32_e32 v109, vcc, 0, v113, vcc
	global_load_dwordx4 v[104:107], v[104:105], off nt
	s_nop 0
	global_load_dwordx4 v[108:111], v[108:109], off nt
	s_waitcnt vmcnt(14)
	v_cvt_pk_bf16_f32 v58, v60, v61
	v_cvt_pk_bf16_f32 v59, v62, v63
	ds_write2_b64 v203, v[56:57], v[58:59] offset1:68
	s_waitcnt vmcnt(13)
	v_cvt_pk_bf16_f32 v56, v68, v69
	v_cvt_pk_bf16_f32 v57, v70, v71
	s_waitcnt vmcnt(12)
	v_cvt_pk_bf16_f32 v58, v72, v73
	v_cvt_pk_bf16_f32 v59, v74, v75
	ds_write2_b64 v203, v[56:57], v[58:59] offset0:136 offset1:204
	s_waitcnt vmcnt(11)
	v_cvt_pk_bf16_f32 v56, v76, v77
	v_cvt_pk_bf16_f32 v57, v78, v79
	s_waitcnt vmcnt(10)
	v_cvt_pk_bf16_f32 v58, v84, v85
	v_cvt_pk_bf16_f32 v59, v86, v87
	ds_write2_b64 v146, v[56:57], v[58:59] offset0:16 offset1:84
	s_waitcnt vmcnt(9)
	v_cvt_pk_bf16_f32 v56, v148, v149
	v_cvt_pk_bf16_f32 v57, v150, v151
	s_waitcnt vmcnt(8)
	v_cvt_pk_bf16_f32 v58, v152, v153
	v_cvt_pk_bf16_f32 v59, v154, v155
	ds_write2_b64 v146, v[56:57], v[58:59] offset0:152 offset1:220
	s_waitcnt lgkmcnt(0)
	ds_read_b128 v[56:59], v204
	ds_read_b128 v[60:63], v204 offset:64
	s_waitcnt lgkmcnt(1)
	v_mfma_f32_16x16x32_bf16 v[56:59], v[4:7], v[56:59], 0
	v_sub_u32_e32 v68, v200, v48
	v_cvt_f32_i32_e32 v72, v68
	ds_read_b128 v[68:71], v204 offset:128
	s_waitcnt lgkmcnt(1)
	v_mfma_f32_16x16x32_bf16 v[56:59], v[0:3], v[60:63], v[56:59]
	v_fma_f32 v149, -v177, v114, v52
	v_sub_u32_e32 v52, v199, v48
	v_sub_u32_e32 v48, v201, v48
	v_cvt_f32_i32_e32 v48, v48
	ds_read_b128 v[60:63], v204 offset:192
	v_cvt_f32_i32_e32 v52, v52
	s_waitcnt lgkmcnt(1)
	v_mfma_f32_16x16x32_bf16 v[56:59], v[12:15], v[68:71], v[56:59]
	v_fma_f32 v148, -v177, v48, v55
	v_or_b32_e32 v48, s48, v187
	v_fma_f32 v152, -v177, v52, v53
	v_fma_f32 v150, -v177, v72, v54
	s_waitcnt lgkmcnt(0)
	v_mfma_f32_16x16x32_bf16 v[52:55], v[8:11], v[60:63], v[56:59]
	s_mov_b32 s42, 0x60000
	s_waitcnt lgkmcnt(0)
	s_waitcnt vmcnt(7)
	v_cvt_pk_bf16_f32 v64, v64, v65
	v_sub_u32_e32 v56, v198, v48
	v_cvt_f32_i32_e32 v151, v56
	v_add_co_u32_e32 v56, vcc, s42, v112
	s_mov_b32 s42, 0x62000
	s_nop 0
	v_addc_co_u32_e32 v57, vcc, 0, v113, vcc
	v_add_co_u32_e32 v60, vcc, s42, v112
	v_cvt_pk_bf16_f32 v65, v66, v67
	s_nop 0
	v_addc_co_u32_e32 v61, vcc, 0, v113, vcc
	v_add_co_u32_e32 v68, vcc, s69, v112
	global_load_dwordx4 v[56:59], v[56:57], off nt
	s_nop 0
	global_load_dwordx4 v[60:63], v[60:61], off nt
	v_addc_co_u32_e32 v69, vcc, 0, v113, vcc
	v_add_co_u32_e32 v72, vcc, s70, v112
	s_waitcnt vmcnt(8)
	v_cvt_pk_bf16_f32 v66, v80, v81
	v_addc_co_u32_e32 v73, vcc, 0, v113, vcc
	v_add_co_u32_e32 v76, vcc, s71, v112
	global_load_dwordx4 v[68:71], v[68:69], off nt
	s_nop 0
	global_load_dwordx4 v[72:75], v[72:73], off nt
	v_addc_co_u32_e32 v77, vcc, 0, v113, vcc
	v_add_co_u32_e32 v84, vcc, s72, v112
	v_cvt_pk_bf16_f32 v67, v82, v83
	s_nop 0
	v_addc_co_u32_e32 v85, vcc, 0, v113, vcc
	v_add_co_u32_e32 v114, vcc, s74, v112
	global_load_dwordx4 v[76:79], v[76:77], off nt
	s_nop 0
	global_load_dwordx4 v[84:87], v[84:85], off nt
	v_addc_co_u32_e32 v115, vcc, 0, v113, vcc
	v_add_co_u32_e32 v158, vcc, s76, v112
	v_fma_f32 v174, -v177, v151, v52
	s_nop 0
	v_addc_co_u32_e32 v159, vcc, 0, v113, vcc
	global_load_dwordx4 v[154:157], v[114:115], off nt
	s_nop 0
	global_load_dwordx4 v[158:161], v[158:159], off nt
	ds_write2_b64 v203, v[64:65], v[66:67] offset1:68
	s_waitcnt vmcnt(13)
	v_cvt_pk_bf16_f32 v64, v88, v89
	v_cvt_pk_bf16_f32 v65, v90, v91
	s_waitcnt vmcnt(12)
	v_cvt_pk_bf16_f32 v66, v92, v93
	v_cvt_pk_bf16_f32 v67, v94, v95
	ds_write2_b64 v203, v[64:65], v[66:67] offset0:136 offset1:204
	s_waitcnt vmcnt(11)
	v_cvt_pk_bf16_f32 v64, v96, v97
	v_add_co_u32_e32 v96, vcc, s77, v112
	s_waitcnt vmcnt(10)
	v_cvt_pk_bf16_f32 v66, v100, v101
	v_addc_co_u32_e32 v97, vcc, 0, v113, vcc
	v_add_co_u32_e32 v100, vcc, s78, v112
	v_cvt_pk_bf16_f32 v65, v98, v99
	v_cvt_pk_bf16_f32 v67, v102, v103
	v_addc_co_u32_e32 v101, vcc, 0, v113, vcc
	ds_write2_b64 v146, v[64:65], v[66:67] offset0:16 offset1:84
	s_waitcnt vmcnt(9)
	v_cvt_pk_bf16_f32 v64, v104, v105
	v_add_co_u32_e32 v104, vcc, s79, v112
	v_cvt_pk_bf16_f32 v65, v106, v107
	s_nop 0
	v_addc_co_u32_e32 v105, vcc, 0, v113, vcc
	s_waitcnt vmcnt(8)
	v_cvt_pk_bf16_f32 v66, v108, v109
	v_cvt_pk_bf16_f32 v67, v110, v111
	v_add_co_u32_e32 v108, vcc, s80, v112
	ds_write2_b64 v146, v[64:65], v[66:67] offset0:152 offset1:220
	s_nop 0
	v_addc_co_u32_e32 v109, vcc, 0, v113, vcc
	s_waitcnt lgkmcnt(0)
	v_add_co_u32_e32 v114, vcc, s81, v112
	ds_read_b128 v[64:67], v204
	ds_read_b128 v[80:83], v204 offset:64
	ds_read_b128 v[88:91], v204 offset:128
	ds_read_b128 v[92:95], v204 offset:192
	v_addc_co_u32_e32 v115, vcc, 0, v113, vcc
	s_waitcnt lgkmcnt(0)
	v_add_co_u32_e32 v166, vcc, s82, v112
	global_load_dwordx4 v[96:99], v[96:97], off nt
	s_nop 0
	global_load_dwordx4 v[100:103], v[100:101], off nt
	v_addc_co_u32_e32 v167, vcc, 0, v113, vcc
	global_load_dwordx4 v[104:107], v[104:105], off nt
	s_nop 0
	global_load_dwordx4 v[108:111], v[108:109], off nt
	s_nop 0
	global_load_dwordx4 v[162:165], v[114:115], off nt
	s_nop 0
	global_load_dwordx4 v[166:169], v[166:167], off nt
	v_add_co_u32_e32 v114, vcc, s83, v112
	s_waitcnt lgkmcnt(3)
	v_mfma_f32_16x16x32_bf16 v[64:67], v[4:7], v[64:67], 0
	v_addc_co_u32_e32 v115, vcc, 0, v113, vcc
	v_add_co_u32_e32 v112, vcc, s84, v112
	global_load_dwordx4 v[170:173], v[114:115], off nt
	s_nop 0
	v_addc_co_u32_e32 v113, vcc, 0, v113, vcc
	global_load_dwordx4 v[112:115], v[112:113], off nt
	s_waitcnt vmcnt(15)
	v_cvt_pk_bf16_f32 v56, v56, v57
	v_cvt_pk_bf16_f32 v57, v58, v59
	s_waitcnt vmcnt(14)
	v_cvt_pk_bf16_f32 v58, v60, v61
	v_cvt_pk_bf16_f32 v59, v62, v63
	s_waitcnt lgkmcnt(2)
	v_mfma_f32_16x16x32_bf16 v[64:67], v[0:3], v[80:83], v[64:67]
	ds_write2_b64 v203, v[56:57], v[58:59] offset1:68
	s_waitcnt vmcnt(13)
	v_cvt_pk_bf16_f32 v56, v68, v69
	v_cvt_pk_bf16_f32 v57, v70, v71
	s_waitcnt vmcnt(12)
	v_cvt_pk_bf16_f32 v58, v72, v73
	v_cvt_pk_bf16_f32 v59, v74, v75
	ds_write2_b64 v203, v[56:57], v[58:59] offset0:136 offset1:204
	s_waitcnt vmcnt(11)
	v_cvt_pk_bf16_f32 v56, v76, v77
	v_cvt_pk_bf16_f32 v57, v78, v79
	s_waitcnt vmcnt(10)
	v_cvt_pk_bf16_f32 v58, v84, v85
	v_cvt_pk_bf16_f32 v59, v86, v87
	v_sub_u32_e32 v52, v199, v48
	v_sub_u32_e32 v151, v200, v48
	v_sub_u32_e32 v48, v201, v48
	ds_write2_b64 v146, v[56:57], v[58:59] offset0:16 offset1:84
	s_waitcnt vmcnt(9)
	v_cvt_pk_bf16_f32 v56, v154, v155
	v_cvt_pk_bf16_f32 v57, v156, v157
	s_waitcnt vmcnt(8)
	v_cvt_pk_bf16_f32 v58, v158, v159
	v_cvt_pk_bf16_f32 v59, v160, v161
	v_cvt_f32_i32_e32 v48, v48
	ds_write2_b64 v146, v[56:57], v[58:59] offset0:152 offset1:220
	v_cvt_f32_i32_e32 v52, v52
	v_cvt_f32_i32_e32 v80, v151
	s_waitcnt lgkmcnt(5)
	v_mfma_f32_16x16x32_bf16 v[64:67], v[12:15], v[88:91], v[64:67]
	s_waitcnt lgkmcnt(0)
	ds_read_b128 v[56:59], v204
	ds_read_b128 v[60:63], v204 offset:64
	v_fma_f32 v240, -v177, v48, v55
	v_or_b32_e32 v48, s48, v188
	v_fma_f32 v175, -v177, v52, v53
	v_fma_f32 v237, -v177, v80, v54
	s_waitcnt lgkmcnt(6)
	v_mfma_f32_16x16x32_bf16 v[52:55], v[8:11], v[92:95], v[64:67]
	s_nop 2
	v_sub_u32_e32 v64, v198, v48
	v_cvt_f32_i32_e32 v64, v64
	s_waitcnt lgkmcnt(1)
	v_mfma_f32_16x16x32_bf16 v[56:59], v[4:7], v[56:59], 0
	s_nop 0
	v_fma_f32 v154, -v177, v64, v52
	v_sub_u32_e32 v64, v200, v48
	v_cvt_f32_i32_e32 v68, v64
	ds_read_b128 v[64:67], v204 offset:128
	s_waitcnt lgkmcnt(1)
	v_mfma_f32_16x16x32_bf16 v[56:59], v[0:3], v[60:63], v[56:59]
	v_sub_u32_e32 v52, v199, v48
	v_sub_u32_e32 v48, v201, v48
	v_cvt_f32_i32_e32 v48, v48
	ds_read_b128 v[60:63], v204 offset:192
	v_cvt_f32_i32_e32 v52, v52
	s_waitcnt lgkmcnt(1)
	v_mfma_f32_16x16x32_bf16 v[56:59], v[12:15], v[64:67], v[56:59]
	v_fma_f32 v242, -v177, v48, v55
	v_or_b32_e32 v48, s48, v189
	v_fma_f32 v156, -v177, v52, v53
	v_fma_f32 v158, -v177, v68, v54
	s_waitcnt lgkmcnt(0)
	v_mfma_f32_16x16x32_bf16 v[52:55], v[8:11], v[60:63], v[56:59]
	s_waitcnt lgkmcnt(0)
	v_sub_u32_e32 v64, v199, v48
	v_cvt_f32_i32_e32 v68, v64
	s_nop 0
	v_sub_u32_e32 v56, v201, v48
	v_cvt_f32_i32_e32 v60, v56
	s_waitcnt vmcnt(7)
	v_cvt_pk_bf16_f32 v56, v96, v97
	v_cvt_pk_bf16_f32 v57, v98, v99
	s_waitcnt vmcnt(6)
	v_cvt_pk_bf16_f32 v58, v100, v101
	v_cvt_pk_bf16_f32 v59, v102, v103
	ds_write2_b64 v203, v[56:57], v[58:59] offset1:68
	s_waitcnt vmcnt(5)
	v_cvt_pk_bf16_f32 v56, v104, v105
	v_cvt_pk_bf16_f32 v57, v106, v107
	s_waitcnt vmcnt(4)
	v_cvt_pk_bf16_f32 v58, v108, v109
	v_cvt_pk_bf16_f32 v59, v110, v111
	ds_write2_b64 v203, v[56:57], v[58:59] offset0:136 offset1:204
	s_waitcnt vmcnt(3)
	v_cvt_pk_bf16_f32 v56, v162, v163
	v_cvt_pk_bf16_f32 v57, v164, v165
	s_waitcnt vmcnt(2)
	v_cvt_pk_bf16_f32 v58, v166, v167
	v_cvt_pk_bf16_f32 v59, v168, v169
	ds_write2_b64 v146, v[56:57], v[58:59] offset0:16 offset1:84
	s_waitcnt vmcnt(1)
	v_cvt_pk_bf16_f32 v56, v170, v171
	v_cvt_pk_bf16_f32 v57, v172, v173
	s_waitcnt vmcnt(0)
	v_cvt_pk_bf16_f32 v58, v112, v113
	v_cvt_pk_bf16_f32 v59, v114, v115
	ds_write2_b64 v146, v[56:57], v[58:59] offset0:152 offset1:220
	s_waitcnt lgkmcnt(0)
	ds_read_b128 v[56:59], v204
	v_fma_f32 v243, -v177, v60, v55
	ds_read_b128 v[60:63], v204 offset:64
	s_waitcnt lgkmcnt(1)
	v_mfma_f32_16x16x32_bf16 v[56:59], v[4:7], v[56:59], 0
	ds_read_b128 v[64:67], v204 offset:128
	v_sub_u32_e32 v55, v200, v48
	v_sub_u32_e32 v48, v198, v48
	s_waitcnt lgkmcnt(1)
	v_mfma_f32_16x16x32_bf16 v[56:59], v[0:3], v[60:63], v[56:59]
	v_cvt_f32_i32_e32 v48, v48
	ds_read_b128 v[60:63], v204 offset:192
	v_cvt_f32_i32_e32 v55, v55
	s_waitcnt lgkmcnt(1)
	v_mfma_f32_16x16x32_bf16 v[56:59], v[12:15], v[64:67], v[56:59]
	v_fma_f32 v157, -v177, v48, v52
	v_or_b32_e32 v48, s48, v190
	v_fma_f32 v146, -v177, v55, v54
	v_fma_f32 v160, -v177, v68, v53
	s_waitcnt lgkmcnt(0)
	v_mfma_f32_16x16x32_bf16 v[52:55], v[8:11], v[60:63], v[56:59]
	v_lshl_add_u64 v[108:109], s[54:55], 0, v[136:137]
	s_waitcnt lgkmcnt(0)
	s_nop 1
	v_sub_u32_e32 v56, v198, v48
	v_sub_u32_e32 v57, v199, v48
	v_sub_u32_e32 v58, v200, v48
	v_sub_u32_e32 v48, v201, v48
	v_cvt_f32_i32_e32 v48, v48
	v_cvt_f32_i32_e32 v56, v56
	v_cvt_f32_i32_e32 v57, v57
	v_cvt_f32_i32_e32 v58, v58
	v_fma_f32 v245, -v177, v48, v55
	v_max_f32_e32 v48, v135, v49
	v_max3_f32 v48, v48, v147, v149
	v_fma_f32 v241, -v177, v56, v52
	v_max3_f32 v48, v48, v174, v154
	v_max3_f32 v48, v48, v157, v241
	ds_swizzle_b32 v102, v48 offset:swizzle(SWAP,1)
	v_fma_f32 v161, -v177, v57, v53
	v_add_co_u32_e32 v56, vcc, s44, v108
	v_fma_f32 v244, -v177, v58, v54
	s_waitcnt lgkmcnt(0)
	v_max_f32_e32 v102, v102, v102
	v_max_f32_e32 v48, v48, v102
	ds_swizzle_b32 v110, v48 offset:swizzle(SWAP,2)
	v_addc_co_u32_e32 v57, vcc, 0, v109, vcc
	v_add_co_u32_e32 v60, vcc, s49, v108
	s_waitcnt lgkmcnt(0)
	v_max_f32_e32 v110, v110, v110
	v_max_f32_e32 v48, v48, v110
	ds_swizzle_b32 v112, v48 offset:swizzle(SWAP,4)
	v_addc_co_u32_e32 v61, vcc, 0, v109, vcc
	v_add_co_u32_e32 v64, vcc, s56, v108
	s_waitcnt lgkmcnt(0)
	v_max_f32_e32 v112, v112, v112
	v_max_f32_e32 v48, v48, v112
	ds_swizzle_b32 v151, v48 offset:swizzle(SWAP,8)
	v_addc_co_u32_e32 v65, vcc, 0, v109, vcc
	v_add_co_u32_e32 v68, vcc, s57, v108
	s_waitcnt lgkmcnt(0)
	v_max3_f32 v48, v145, v48, v151
	v_max_f32_e32 v151, v133, v50
	v_max3_f32 v151, v151, v141, v152
	v_max3_f32 v151, v151, v175, v156
	v_max3_f32 v151, v151, v160, v161
	ds_swizzle_b32 v153, v151 offset:swizzle(SWAP,1)
	v_sub_f32_e32 v135, v135, v48
	v_exp_f32_e32 v159, v135
	v_sub_f32_e32 v49, v49, v48
	v_exp_f32_e32 v155, v49
	s_waitcnt lgkmcnt(0)
	v_max_f32_e32 v135, v153, v153
	v_max_f32_e32 v135, v151, v135
	v_sub_f32_e32 v49, v147, v48
	ds_swizzle_b32 v147, v135 offset:swizzle(SWAP,2)
	v_exp_f32_e32 v153, v49
	v_sub_f32_e32 v49, v149, v48
	v_exp_f32_e32 v151, v49
	v_sub_f32_e32 v49, v174, v48
	s_waitcnt lgkmcnt(0)
	v_max_f32_e32 v147, v147, v147
	v_max_f32_e32 v135, v135, v147
	ds_swizzle_b32 v162, v135 offset:swizzle(SWAP,4)
	v_exp_f32_e32 v149, v49
	v_sub_f32_e32 v49, v154, v48
	v_exp_f32_e32 v147, v49
	v_sub_f32_e32 v49, v157, v48
	s_waitcnt lgkmcnt(0)
	v_max_f32_e32 v154, v162, v162
	v_max_f32_e32 v157, v130, v51
	v_addc_co_u32_e32 v69, vcc, 0, v109, vcc
	v_max_f32_e32 v135, v135, v154
	v_max3_f32 v157, v157, v140, v150
	v_add_co_u32_e32 v72, vcc, s58, v108
	ds_swizzle_b32 v154, v135 offset:swizzle(SWAP,8)
	v_max3_f32 v157, v157, v237, v158
	v_addc_co_u32_e32 v73, vcc, 0, v109, vcc
	v_max3_f32 v162, v157, v146, v244
	v_add_co_u32_e32 v76, vcc, s59, v108
	ds_swizzle_b32 v163, v162 offset:swizzle(SWAP,1)
	s_nop 0
	v_addc_co_u32_e32 v77, vcc, 0, v109, vcc
	v_add_co_u32_e32 v80, vcc, s60, v108
	v_exp_f32_e32 v157, v49
	s_nop 0
	v_addc_co_u32_e32 v81, vcc, 0, v109, vcc
	s_waitcnt lgkmcnt(1)
	v_max3_f32 v49, v144, v135, v154
	v_add_co_u32_e32 v84, vcc, s61, v108
	v_sub_f32_e32 v133, v133, v49
	s_nop 0
	v_addc_co_u32_e32 v85, vcc, 0, v109, vcc
	v_exp_f32_e32 v174, v133
	s_waitcnt lgkmcnt(0)
	v_max_f32_e32 v133, v163, v163
	v_add_co_u32_e32 v88, vcc, s62, v108
	v_max_f32_e32 v133, v162, v133
	s_nop 0
	v_addc_co_u32_e32 v89, vcc, 0, v109, vcc
	ds_swizzle_b32 v135, v133 offset:swizzle(SWAP,2)
	v_add_co_u32_e32 v92, vcc, s63, v108
	v_sub_f32_e32 v50, v50, v49
	s_nop 0
	v_addc_co_u32_e32 v93, vcc, 0, v109, vcc
	v_add_co_u32_e32 v96, vcc, s64, v108
	v_exp_f32_e32 v172, v50
	s_nop 0
	v_addc_co_u32_e32 v97, vcc, 0, v109, vcc
	v_sub_f32_e32 v50, v141, v49
	v_add_co_u32_e32 v100, vcc, s65, v108
	v_exp_f32_e32 v170, v50
	s_waitcnt lgkmcnt(0)
	v_max_f32_e32 v50, v135, v135
	v_addc_co_u32_e32 v101, vcc, 0, v109, vcc
	v_max_f32_e32 v50, v133, v50
	v_add_co_u32_e32 v104, vcc, s66, v108
	ds_swizzle_b32 v133, v50 offset:swizzle(SWAP,4)
	s_nop 0
	v_addc_co_u32_e32 v105, vcc, 0, v109, vcc
	v_add_co_u32_e32 v110, vcc, s67, v108
	s_waitcnt lgkmcnt(0)
	v_max_f32_e32 v133, v133, v133
	v_addc_co_u32_e32 v111, vcc, 0, v109, vcc
	v_add_co_u32_e32 v112, vcc, s68, v108
	global_load_dwordx4 v[52:55], v[108:109], off nt
	s_nop 0
	global_load_dwordx4 v[56:59], v[56:57], off nt
	v_addc_co_u32_e32 v113, vcc, 0, v109, vcc
	global_load_dwordx4 v[60:63], v[60:61], off nt
	s_nop 0
	global_load_dwordx4 v[64:67], v[64:65], off nt
	s_nop 0
	global_load_dwordx4 v[68:71], v[68:69], off nt
	s_nop 0
	global_load_dwordx4 v[72:75], v[72:73], off nt
	s_nop 0
	global_load_dwordx4 v[76:79], v[76:77], off nt
	s_nop 0
	global_load_dwordx4 v[80:83], v[80:81], off nt
	s_nop 0
	global_load_dwordx4 v[84:87], v[84:85], off nt
	s_nop 0
	global_load_dwordx4 v[88:91], v[88:89], off nt
	s_nop 0
	global_load_dwordx4 v[92:95], v[92:93], off nt
	s_nop 0
	global_load_dwordx4 v[96:99], v[96:97], off nt
	s_nop 0
	global_load_dwordx4 v[100:103], v[100:101], off nt
	s_nop 0
	global_load_dwordx4 v[104:107], v[104:105], off nt
	s_nop 0
	global_load_dwordx4 v[108:111], v[110:111], off nt
	s_nop 0
	global_load_dwordx4 v[112:115], v[112:113], off nt
	v_max_f32_e32 v50, v50, v133
	ds_swizzle_b32 v133, v50 offset:swizzle(SWAP,8)
	v_sub_f32_e32 v135, v152, v49
	v_exp_f32_e32 v168, v135
	v_sub_f32_e32 v135, v175, v49
	v_exp_f32_e32 v166, v135
	s_waitcnt lgkmcnt(0)
	v_max3_f32 v50, v143, v50, v133
	v_sub_f32_e32 v51, v51, v50
	v_sub_f32_e32 v135, v156, v49
	v_exp_f32_e32 v173, v51
	v_sub_f32_e32 v51, v161, v49
	v_exp_f32_e32 v164, v135
	v_sub_f32_e32 v135, v160, v49
	v_exp_f32_e32 v160, v51
	v_sub_f32_e32 v51, v140, v50
	v_exp_f32_e32 v171, v51
	v_sub_f32_e32 v51, v150, v50
	v_exp_f32_e32 v169, v51
	v_sub_f32_e32 v51, v237, v50
	v_exp_f32_e32 v167, v51
	v_sub_f32_e32 v51, v158, v50
	v_exp_f32_e32 v165, v51
	v_max_f32_e32 v51, v131, v132
	v_max3_f32 v51, v51, v134, v148
	v_max3_f32 v51, v51, v240, v242
	v_sub_f32_e32 v130, v130, v50
	v_max3_f32 v51, v51, v243, v245
	v_exp_f32_e32 v175, v130
	ds_swizzle_b32 v130, v51 offset:swizzle(SWAP,1)
	v_sub_f32_e32 v133, v146, v50
	v_exp_f32_e32 v163, v133
	v_pk_add_f32 v[238:239], v[174:175], 0 op_sel_hi:[1,0]
	v_sub_f32_e32 v133, v244, v50
	s_waitcnt lgkmcnt(0)
	v_max_f32_e32 v130, v130, v130
	v_max_f32_e32 v51, v51, v130
	ds_swizzle_b32 v130, v51 offset:swizzle(SWAP,2)
	v_pk_add_f32 v[238:239], v[172:173], v[238:239]
	v_exp_f32_e32 v162, v135
	v_exp_f32_e32 v161, v133
	v_pk_add_f32 v[140:141], v[170:171], v[238:239]
	s_waitcnt lgkmcnt(0)
	v_max_f32_e32 v130, v130, v130
	v_max_f32_e32 v51, v51, v130
	ds_swizzle_b32 v130, v51 offset:swizzle(SWAP,4)
	v_pk_add_f32 v[140:141], v[168:169], v[140:141]
	v_sub_f32_e32 v145, v145, v48
	v_pk_add_f32 v[140:141], v[166:167], v[140:141]
	s_waitcnt lgkmcnt(0)
	v_max_f32_e32 v130, v130, v130
	v_max_f32_e32 v51, v51, v130
	ds_swizzle_b32 v133, v51 offset:swizzle(SWAP,8)
	v_pk_add_f32 v[140:141], v[164:165], v[140:141]
	v_sub_f32_e32 v130, v241, v48
	v_pk_add_f32 v[140:141], v[162:163], v[140:141]
	v_exp_f32_e32 v241, v130
	v_pk_add_f32 v[140:141], v[160:161], v[140:141]
	s_waitcnt lgkmcnt(0)
	v_max3_f32 v51, v142, v51, v133
	ds_swizzle_b32 v238, v140 offset:swizzle(SWAP,1)
	ds_swizzle_b32 v239, v141 offset:swizzle(SWAP,1)
	v_sub_f32_e32 v131, v131, v51
	v_exp_f32_e32 v158, v131
	v_sub_f32_e32 v131, v132, v51
	v_exp_f32_e32 v154, v131
	v_sub_f32_e32 v131, v134, v51
	v_exp_f32_e32 v152, v131
	v_sub_f32_e32 v131, v148, v51
	v_exp_f32_e32 v150, v131
	v_sub_f32_e32 v131, v240, v51
	s_waitcnt lgkmcnt(0)
	v_pk_add_f32 v[140:141], v[140:141], v[238:239]
	v_pk_add_f32 v[238:239], v[158:159], 0 op_sel_hi:[1,0]
	v_exp_f32_e32 v148, v131
	v_sub_f32_e32 v131, v242, v51
	v_pk_add_f32 v[238:239], v[154:155], v[238:239]
	v_exp_f32_e32 v146, v131
	v_sub_f32_e32 v131, v243, v51
	v_exp_f32_e32 v156, v131
	v_sub_f32_e32 v131, v245, v51
	v_pk_add_f32 v[134:135], v[152:153], v[238:239]
	v_exp_f32_e32 v240, v131
	v_pk_add_f32 v[134:135], v[150:151], v[134:135]
	v_cvt_pk_bf16_f32 v159, v159, s0
	v_pk_add_f32 v[134:135], v[148:149], v[134:135]
	ds_write_b16 v205, v159 offset:8192
	v_pk_add_f32 v[134:135], v[146:147], v[134:135]
	v_cvt_pk_bf16_f32 v159, v174, s0
	v_pk_add_f32 v[134:135], v[156:157], v[134:135]
	ds_write_b16 v206, v159 offset:8192
	v_pk_add_f32 v[134:135], v[240:241], v[134:135]
	ds_swizzle_b32 v239, v135 offset:swizzle(SWAP,1)
	ds_swizzle_b32 v238, v134 offset:swizzle(SWAP,1)
	v_cvt_pk_bf16_f32 v159, v175, s0
	v_cvt_pk_bf16_f32 v158, v158, s0
	v_cvt_pk_bf16_f32 v155, v155, s0
	v_exp_f32_e32 v130, v145
	v_sub_f32_e32 v131, v144, v49
	s_waitcnt lgkmcnt(0)
	v_pk_add_f32 v[144:145], v[134:135], v[238:239]
	ds_write_b16 v207, v159 offset:8192
	ds_write_b16 v208, v158 offset:8192
	ds_write_b16 v209, v155 offset:8192
	v_cvt_pk_bf16_f32 v155, v172, s0
	ds_swizzle_b32 v132, v140 offset:swizzle(SWAP,2)
	ds_swizzle_b32 v133, v141 offset:swizzle(SWAP,2)
	ds_swizzle_b32 v239, v145 offset:swizzle(SWAP,2)
	ds_swizzle_b32 v238, v144 offset:swizzle(SWAP,2)
	ds_write_b16 v210, v155 offset:8192
	v_cvt_pk_bf16_f32 v155, v173, s0
	v_cvt_pk_bf16_f32 v154, v154, s0
	v_cvt_pk_bf16_f32 v153, v153, s0
	ds_write_b16 v211, v155 offset:8192
	ds_write_b16 v212, v154 offset:8192
	ds_write_b16 v213, v153 offset:8192
	v_cvt_pk_bf16_f32 v153, v170, s0
	ds_write_b16 v214, v153 offset:8192
	v_cvt_pk_bf16_f32 v153, v171, s0
	v_cvt_pk_bf16_f32 v152, v152, s0
	v_cvt_pk_bf16_f32 v151, v151, s0
	ds_write_b16 v215, v153 offset:8192
	ds_write_b16 v216, v152 offset:8192
	ds_write_b16 v217, v151 offset:8192
	v_cvt_pk_bf16_f32 v151, v168, s0
	ds_write_b16 v218, v151 offset:8192
	v_cvt_pk_bf16_f32 v151, v169, s0
	v_cvt_pk_bf16_f32 v150, v150, s0
	v_cvt_pk_bf16_f32 v149, v149, s0
	s_waitcnt lgkmcnt(11)
	v_pk_add_f32 v[132:133], v[140:141], v[132:133]
	s_waitcnt lgkmcnt(9)
	v_pk_add_f32 v[144:145], v[144:145], v[238:239]
	ds_write_b16 v219, v151 offset:8192
	ds_write_b16 v220, v150 offset:8192
	ds_write_b16 v221, v149 offset:8192
	v_cvt_pk_bf16_f32 v149, v166, s0
	ds_swizzle_b32 v140, v132 offset:swizzle(SWAP,4)
	ds_swizzle_b32 v141, v133 offset:swizzle(SWAP,4)
	ds_swizzle_b32 v239, v145 offset:swizzle(SWAP,4)
	ds_swizzle_b32 v238, v144 offset:swizzle(SWAP,4)
	ds_write_b16 v222, v149 offset:8192
	v_cvt_pk_bf16_f32 v149, v167, s0
	v_cvt_pk_bf16_f32 v148, v148, s0
	v_cvt_pk_bf16_f32 v147, v147, s0
	ds_write_b16 v223, v149 offset:8192
	ds_write_b16 v224, v148 offset:8192
	ds_write_b16 v225, v147 offset:8192
	v_cvt_pk_bf16_f32 v147, v164, s0
	v_cvt_pk_bf16_f32 v146, v146, s0
	ds_write_b16 v226, v147 offset:8192
	v_cvt_pk_bf16_f32 v147, v165, s0
	ds_write_b16 v228, v146 offset:8192
	v_cvt_pk_bf16_f32 v146, v157, s0
	ds_write_b16 v227, v147 offset:8192
	ds_write_b16 v229, v146 offset:8192
	v_cvt_pk_bf16_f32 v146, v162, s0
	ds_write_b16 v230, v146 offset:8192
	v_cvt_pk_bf16_f32 v146, v163, s0
	v_sub_f32_e32 v134, v143, v50
	s_waitcnt lgkmcnt(11)
	v_pk_add_f32 v[132:133], v[132:133], v[140:141]
	v_sub_f32_e32 v135, v142, v51
	s_waitcnt lgkmcnt(9)
	v_pk_add_f32 v[142:143], v[144:145], v[238:239]
	ds_write_b16 v231, v146 offset:8192
	v_cvt_pk_bf16_f32 v146, v156, s0
	v_exp_f32_e32 v131, v131
	v_exp_f32_e32 v134, v134
	ds_swizzle_b32 v140, v132 offset:swizzle(SWAP,8)
	ds_swizzle_b32 v141, v133 offset:swizzle(SWAP,8)
	v_exp_f32_e32 v135, v135
	ds_swizzle_b32 v145, v143 offset:swizzle(SWAP,8)
	ds_swizzle_b32 v144, v142 offset:swizzle(SWAP,8)
	ds_write_b16 v232, v146 offset:8192
	v_cvt_pk_bf16_f32 v146, v241, s0
	ds_write_b16 v233, v146 offset:8192
	v_cvt_pk_bf16_f32 v146, v160, s0
	ds_write_b16 v234, v146 offset:8192
	v_cvt_pk_bf16_f32 v146, v161, s0
	ds_write_b16 v235, v146 offset:8192
	v_cvt_pk_bf16_f32 v146, v240, s0
	v_pk_mul_f32 v[46:47], v[46:47], v[134:135]
	v_pk_mul_f32 v[44:45], v[44:45], v[130:131]
	v_pk_mul_f32 v[42:43], v[42:43], v[134:135]
	v_pk_mul_f32 v[40:41], v[40:41], v[130:131]
	v_pk_mul_f32 v[38:39], v[38:39], v[134:135]
	v_pk_mul_f32 v[36:37], v[36:37], v[130:131]
	v_pk_mul_f32 v[34:35], v[34:35], v[134:135]
	v_pk_mul_f32 v[32:33], v[32:33], v[130:131]
	v_pk_mul_f32 v[30:31], v[30:31], v[134:135]
	v_pk_mul_f32 v[28:29], v[28:29], v[130:131]
	v_pk_mul_f32 v[26:27], v[26:27], v[134:135]
	v_pk_mul_f32 v[24:25], v[24:25], v[130:131]
	v_pk_mul_f32 v[22:23], v[22:23], v[134:135]
	v_pk_mul_f32 v[20:21], v[20:21], v[130:131]
	v_pk_mul_f32 v[18:19], v[18:19], v[134:135]
	v_pk_mul_f32 v[16:17], v[16:17], v[130:131]
	ds_write_b16 v236, v146 offset:8192
	v_lshl_add_u64 v[146:147], v[124:125], 0, s[52:53]
	s_mov_b64 s[52:53], 0
	v_mov_b32_e32 v148, v202
	s_branch .LBB0_1612
